# softmax row-sum add chain moved into the PV MFMA shadows in both attention bodies (same summation order), on top of lean dispatch + pipelined conversion
# speedup vs baseline: 1.0065x; 1.0065x over previous
.LBB0_534:
	ds_read_b64_tr_b16 v[204:205], v241 offset:30720
	ds_read_b64_tr_b16 v[242:243], v241 offset:30784
	ds_read_b64_tr_b16 v[246:247], v241 offset:30848
	ds_read_b64_tr_b16 v[250:251], v241 offset:30912
	ds_read_b64_tr_b16 v[206:207], v241 offset:33280
	ds_read_b64_tr_b16 v[244:245], v241 offset:33344
	ds_read_b64_tr_b16 v[248:249], v241 offset:33408
	ds_read_b64_tr_b16 v[252:253], v241 offset:33472
	v_exp_f32_e32 v82, v82
	v_exp_f32_e32 v83, v83
	v_exp_f32_e32 v84, v84
	v_exp_f32_e32 v85, v85
	v_exp_f32_e32 v86, v86
	v_exp_f32_e32 v87, v87
	v_exp_f32_e32 v88, v88
	v_exp_f32_e32 v89, v89
	v_cvt_pk_bf16_f32 v194, v82, v83
	v_cvt_pk_bf16_f32 v195, v84, v85
	v_cvt_pk_bf16_f32 v196, v86, v87
	v_cvt_pk_bf16_f32 v197, v88, v89
	v_exp_f32_e32 v90, v90
	s_waitcnt lgkmcnt(11)
	v_mfma_f32_32x32x16_bf16 v[50:65], v[178:181], v[194:197], v[50:65]
	v_exp_f32_e32 v91, v91
	v_exp_f32_e32 v92, v92
	v_exp_f32_e32 v93, v93
	v_exp_f32_e32 v94, v94
	v_exp_f32_e32 v95, v95
	v_exp_f32_e32 v96, v96
	v_exp_f32_e32 v97, v97
	s_waitcnt lgkmcnt(10)
	v_mfma_f32_32x32x16_bf16 v[34:49], v[174:177], v[194:197], v[34:49]
	v_exp_f32_e32 v66, v66
	v_exp_f32_e32 v67, v67
	v_exp_f32_e32 v68, v68
	v_exp_f32_e32 v69, v69
	v_exp_f32_e32 v70, v70
	v_exp_f32_e32 v71, v71
	v_exp_f32_e32 v72, v72
	s_waitcnt lgkmcnt(9)
	v_mfma_f32_32x32x16_bf16 v[18:33], v[170:173], v[194:197], v[18:33]
	v_exp_f32_e32 v73, v73
	s_waitcnt lgkmcnt(8)
	v_mfma_f32_32x32x16_bf16 v[2:17], v[166:169], v[194:197], v[2:17]
	ds_read_b64_tr_b16 v[166:167], v241 offset:35840
	ds_read_b64_tr_b16 v[170:171], v241 offset:35904
	ds_read_b64_tr_b16 v[174:175], v241 offset:35968
	ds_read_b64_tr_b16 v[178:179], v241 offset:36032
	ds_read_b64_tr_b16 v[168:169], v241 offset:38400
	ds_read_b64_tr_b16 v[172:173], v241 offset:38464
	ds_read_b64_tr_b16 v[176:177], v241 offset:38528
	ds_read_b64_tr_b16 v[180:181], v241 offset:38592
	v_cvt_pk_bf16_f32 v194, v90, v91
	v_cvt_pk_bf16_f32 v195, v92, v93
	v_cvt_pk_bf16_f32 v196, v94, v95
	v_cvt_pk_bf16_f32 v197, v96, v97
	v_exp_f32_e32 v74, v74
	s_waitcnt lgkmcnt(11)
	v_mfma_f32_32x32x16_bf16 v[50:65], v[204:207], v[194:197], v[50:65]
	v_exp_f32_e32 v75, v75
	v_exp_f32_e32 v76, v76
	v_exp_f32_e32 v77, v77
	v_exp_f32_e32 v78, v78
	v_exp_f32_e32 v79, v79
	v_exp_f32_e32 v80, v80
	v_exp_f32_e32 v81, v81
	s_waitcnt lgkmcnt(10)
	v_mfma_f32_32x32x16_bf16 v[34:49], v[242:245], v[194:197], v[34:49]
	v_add_f32_e32 v0, 0, v82
	v_add_f32_e32 v0, v83, v0
	v_add_f32_e32 v0, v84, v0
	v_add_f32_e32 v0, v85, v0
	s_waitcnt lgkmcnt(9)
	v_mfma_f32_32x32x16_bf16 v[18:33], v[246:249], v[194:197], v[18:33]
	v_add_f32_e32 v0, v86, v0
	v_add_f32_e32 v0, v87, v0
	v_add_f32_e32 v0, v88, v0
	v_add_f32_e32 v0, v89, v0
	s_waitcnt lgkmcnt(8)
	v_mfma_f32_32x32x16_bf16 v[2:17], v[250:253], v[194:197], v[2:17]
	v_add_f32_e32 v0, v90, v0
	v_add_f32_e32 v0, v91, v0
	v_add_f32_e32 v0, v92, v0
	v_add_f32_e32 v0, v93, v0
	ds_read_b64_tr_b16 v[194:195], v241 offset:40960
	ds_read_b64_tr_b16 v[204:205], v241 offset:41024
	ds_read_b64_tr_b16 v[242:243], v241 offset:41088
	ds_read_b64_tr_b16 v[246:247], v241 offset:41152
	ds_read_b64_tr_b16 v[196:197], v241 offset:43520
	ds_read_b64_tr_b16 v[206:207], v241 offset:43584
	ds_read_b64_tr_b16 v[244:245], v241 offset:43648
	ds_read_b64_tr_b16 v[248:249], v241 offset:43712
	v_cvt_pk_bf16_f32 v250, v66, v67
	v_cvt_pk_bf16_f32 v251, v68, v69
	v_cvt_pk_bf16_f32 v252, v70, v71
	v_cvt_pk_bf16_f32 v253, v72, v73
	s_waitcnt lgkmcnt(11)
	v_mfma_f32_32x32x16_bf16 v[50:65], v[166:169], v[250:253], v[50:65]
	v_add_f32_e32 v0, v94, v0
	v_add_f32_e32 v0, v95, v0
	v_add_f32_e32 v0, v96, v0
	v_add_f32_e32 v0, v97, v0
	s_waitcnt lgkmcnt(10)
	v_mfma_f32_32x32x16_bf16 v[34:49], v[170:173], v[250:253], v[34:49]
	v_add_f32_e32 v0, v66, v0
	v_add_f32_e32 v0, v67, v0
	v_add_f32_e32 v0, v68, v0
	v_add_f32_e32 v0, v69, v0
	s_waitcnt lgkmcnt(9)
	v_mfma_f32_32x32x16_bf16 v[18:33], v[174:177], v[250:253], v[18:33]
	v_add_f32_e32 v0, v70, v0
	v_add_f32_e32 v0, v71, v0
	v_add_f32_e32 v0, v72, v0
	v_add_f32_e32 v0, v73, v0
	s_waitcnt lgkmcnt(8)
	v_mfma_f32_32x32x16_bf16 v[2:17], v[178:181], v[250:253], v[2:17]
	v_add_f32_e32 v0, v74, v0
	v_add_f32_e32 v0, v75, v0
	v_add_f32_e32 v0, v76, v0
	v_add_f32_e32 v0, v77, v0
	v_cvt_pk_bf16_f32 v166, v74, v75
	v_cvt_pk_bf16_f32 v167, v76, v77
	v_cvt_pk_bf16_f32 v168, v78, v79
	v_cvt_pk_bf16_f32 v169, v80, v81
	s_waitcnt lgkmcnt(3)
	v_mfma_f32_32x32x16_bf16 v[50:65], v[194:197], v[166:169], v[50:65]
	v_add_f32_e32 v0, v78, v0
	v_add_f32_e32 v0, v79, v0
	v_add_f32_e32 v0, v80, v0
	v_add_f32_e32 v0, v81, v0
	s_waitcnt lgkmcnt(2)
	v_mfma_f32_32x32x16_bf16 v[34:49], v[204:207], v[166:169], v[34:49]
	s_waitcnt lgkmcnt(1)
	v_mfma_f32_32x32x16_bf16 v[18:33], v[242:245], v[166:169], v[18:33]
	s_waitcnt lgkmcnt(0)
	v_mfma_f32_32x32x16_bf16 v[2:17], v[246:249], v[166:169], v[2:17]
	s_mov_b64 s[30:31], -1
	s_and_b64 vcc, exec, s[26:27]
	s_cbranch_vccz .LBB0_536
	s_setprio 0
	s_mov_b64 s[30:31], 0
.LBB0_536:
	s_andn2_b64 vcc, exec, s[30:31]
	v_add_f32_e32 v239, v239, v0
	s_cbranch_vccnz .LBB0_517
	s_setprio 1
	s_branch .LBB0_517

.LBB0_811:
	v_exp_f32_e32 v48, v48
	v_exp_f32_e32 v49, v49
	v_exp_f32_e32 v50, v50
	v_exp_f32_e32 v51, v51
	v_exp_f32_e32 v52, v52
	v_exp_f32_e32 v53, v53
	v_exp_f32_e32 v54, v54
	v_exp_f32_e32 v55, v55
	ds_read_b64_tr_b16 v[12:13], v10 offset:12288
	ds_read_b64_tr_b16 v[14:15], v10 offset:13824
	ds_read_b64_tr_b16 v[138:139], v10 offset:13888
	ds_read_b64_tr_b16 v[136:137], v10 offset:12352
	v_cvt_pk_bf16_f32 v140, v48, v49
	v_cvt_pk_bf16_f32 v141, v50, v51
	v_cvt_pk_bf16_f32 v142, v52, v53
	v_cvt_pk_bf16_f32 v143, v54, v55
	v_exp_f32_e32 v56, v56
	s_waitcnt lgkmcnt(6)
	v_mfma_f32_32x32x16_bf16 v[32:47], v[6:9], v[140:143], v[32:47]
	v_exp_f32_e32 v57, v57
	v_exp_f32_e32 v58, v58
	v_exp_f32_e32 v59, v59
	v_exp_f32_e32 v60, v60
	v_exp_f32_e32 v61, v61
	v_exp_f32_e32 v62, v62
	v_exp_f32_e32 v63, v63
	s_waitcnt lgkmcnt(4)
	v_mfma_f32_32x32x16_bf16 v[16:31], v[2:5], v[140:143], v[16:31]
	v_exp_f32_e32 v64, v64
	v_exp_f32_e32 v65, v65
	v_exp_f32_e32 v66, v66
	v_exp_f32_e32 v67, v67
	v_exp_f32_e32 v68, v68
	v_exp_f32_e32 v69, v69
	v_exp_f32_e32 v70, v70
	v_exp_f32_e32 v71, v71
	ds_read_b64_tr_b16 v[2:3], v10 offset:15360
	ds_read_b64_tr_b16 v[4:5], v10 offset:16896
	ds_read_b64_tr_b16 v[8:9], v10 offset:16960
	ds_read_b64_tr_b16 v[6:7], v10 offset:15424
	v_cvt_pk_bf16_f32 v140, v56, v57
	v_cvt_pk_bf16_f32 v141, v58, v59
	v_cvt_pk_bf16_f32 v142, v60, v61
	v_cvt_pk_bf16_f32 v143, v62, v63
	v_exp_f32_e32 v72, v72
	s_waitcnt lgkmcnt(6)
	v_mfma_f32_32x32x16_bf16 v[32:47], v[12:15], v[140:143], v[32:47]
	v_exp_f32_e32 v73, v73
	v_exp_f32_e32 v74, v74
	v_exp_f32_e32 v75, v75
	v_exp_f32_e32 v76, v76
	v_exp_f32_e32 v77, v77
	v_exp_f32_e32 v78, v78
	v_exp_f32_e32 v79, v79
	s_waitcnt lgkmcnt(4)
	v_mfma_f32_32x32x16_bf16 v[16:31], v[136:139], v[140:143], v[16:31]
	v_add_f32_e32 v0, 0, v48
	v_add_f32_e32 v0, v49, v0
	v_add_f32_e32 v0, v50, v0
	v_add_f32_e32 v0, v51, v0
	v_add_f32_e32 v0, v52, v0
	v_add_f32_e32 v0, v53, v0
	ds_read_b64_tr_b16 v[12:13], v10 offset:18432
	ds_read_b64_tr_b16 v[14:15], v10 offset:19968
	ds_read_b64_tr_b16 v[138:139], v10 offset:20032
	ds_read_b64_tr_b16 v[136:137], v10 offset:18496
	v_cvt_pk_bf16_f32 v140, v64, v65
	v_cvt_pk_bf16_f32 v141, v66, v67
	v_cvt_pk_bf16_f32 v142, v68, v69
	v_cvt_pk_bf16_f32 v143, v70, v71
	s_waitcnt lgkmcnt(6)
	v_mfma_f32_32x32x16_bf16 v[32:47], v[2:5], v[140:143], v[32:47]
	v_add_f32_e32 v0, v54, v0
	v_add_f32_e32 v0, v55, v0
	v_add_f32_e32 v0, v56, v0
	v_add_f32_e32 v0, v57, v0
	v_add_f32_e32 v0, v58, v0
	v_add_f32_e32 v0, v59, v0
	s_waitcnt lgkmcnt(4)
	v_mfma_f32_32x32x16_bf16 v[16:31], v[6:9], v[140:143], v[16:31]
	v_add_f32_e32 v0, v60, v0
	v_add_f32_e32 v0, v61, v0
	v_add_f32_e32 v0, v62, v0
	v_add_f32_e32 v0, v63, v0
	v_add_f32_e32 v0, v64, v0
	v_add_f32_e32 v0, v65, v0
	v_cvt_pk_bf16_f32 v2, v72, v73
	v_cvt_pk_bf16_f32 v3, v74, v75
	v_cvt_pk_bf16_f32 v4, v76, v77
	v_cvt_pk_bf16_f32 v5, v78, v79
	s_waitcnt lgkmcnt(2)
	v_mfma_f32_32x32x16_bf16 v[32:47], v[12:15], v[2:5], v[32:47]
	v_add_f32_e32 v0, v66, v0
	v_add_f32_e32 v0, v67, v0
	v_add_f32_e32 v0, v68, v0
	v_add_f32_e32 v0, v69, v0
	v_add_f32_e32 v0, v70, v0
	v_add_f32_e32 v0, v71, v0
	s_waitcnt lgkmcnt(0)
	v_mfma_f32_32x32x16_bf16 v[16:31], v[136:139], v[2:5], v[16:31]
	v_add_f32_e32 v0, v72, v0
	v_add_f32_e32 v0, v73, v0
	v_add_f32_e32 v0, v74, v0
	v_add_f32_e32 v0, v75, v0
	v_add_f32_e32 v0, v76, v0
	v_add_f32_e32 v0, v77, v0
	s_mov_b64 s[28:29], -1
	s_and_b64 vcc, exec, s[24:25]
	s_cbranch_vccz .LBB0_813
	s_setprio 0
	s_mov_b64 s[28:29], 0
.LBB0_813:
	v_add_f32_e32 v0, v78, v0
	v_add_f32_e32 v0, v79, v0
	s_andn2_b64 vcc, exec, s[28:29]
	v_add_f32_e32 v117, v117, v0
	s_cbranch_vccnz .LBB0_794
	s_setprio 1
	s_branch .LBB0_794
